# tr_item nvalid variant (WMIX weight items): 32 masked row loads issued together instead of load/wait/store x32, both convert_layer instances
# speedup vs baseline: 1.0186x; 1.0077x over previous
; #define LAS __attribute__((address_space(3)))
; #define LDS_WAIT() asm volatile("s_waitcnt lgkmcnt(0)" ::: "memory")
; __device__ __forceinline__ void tr_item(const float* W, int ldw, int src_col, int nvalid, int k0, bf16_t* WT, int ldt, int dst_row, int dst_k, LAS float* scr, int lane) {
; #pragma unroll 8
;     for (int i = 0; i < 32; ++i) { const int kk = 2 * i + (lane >> 5), c = lane & 31; scr[kk * 33 + c] = (c < nvalid) ? W[(size_t)(k0 + kk) * ldw + src_col + c] : 0.f; }
;     LDS_WAIT();
; __device__ __forceinline__ void convert_layer(const Ctx& C, int l) {
;     ...
;         if (r < 1792) { const int kb = r / 112, nb = r % 112; int src = 0, nv = 0;
;             if (nb < 88) { src = nb * 32; nv = 32; } else if (nb < 104) { src = 2840 + (nb - 88) * 32; nv = 32; } else if (nb == 104) { src = 2816; nv = 24; }
;             tr_item(INF(10, l, DM * 6424), 6424, src, nv, kb * 64, (bf16_t*)(ws + WS_WMIX), DM, nb * 32, 0, scr, lane); continue; } r -= 1792;
.LBB0_79:
	v_mov_b32_e32 v132, 0
	v_mov_b32_e32 v133, 0
	v_mov_b32_e32 v134, 0
	v_mov_b32_e32 v135, 0
	v_mov_b32_e32 v136, 0
	v_mov_b32_e32 v137, 0
	v_mov_b32_e32 v138, 0
	v_mov_b32_e32 v139, 0
	v_mov_b32_e32 v140, 0
	v_mov_b32_e32 v141, 0
	v_mov_b32_e32 v142, 0
	v_mov_b32_e32 v143, 0
	v_mov_b32_e32 v144, 0
	v_mov_b32_e32 v145, 0
	v_mov_b32_e32 v146, 0
	v_mov_b32_e32 v147, 0
	v_mov_b32_e32 v148, 0
	v_mov_b32_e32 v149, 0
	v_mov_b32_e32 v150, 0
	v_mov_b32_e32 v151, 0
	v_mov_b32_e32 v152, 0
	v_mov_b32_e32 v153, 0
	v_mov_b32_e32 v154, 0
	v_mov_b32_e32 v155, 0
	v_mov_b32_e32 v156, 0
	v_mov_b32_e32 v157, 0
	v_mov_b32_e32 v158, 0
	v_mov_b32_e32 v159, 0
	v_mov_b32_e32 v160, 0
	v_mov_b32_e32 v161, 0
	v_mov_b32_e32 v162, 0
	v_mov_b32_e32 v163, 0
	s_and_saveexec_b64 s[2:3], s[4:5]
	v_lshl_add_u64 v[78:79], v[64:65], 0, s[6:7]
	global_load_dword v132, v[78:79], off
	v_lshl_add_u64 v[78:79], v[62:63], 0, s[6:7]
	global_load_dword v133, v[78:79], off
	v_lshl_add_u64 v[78:79], v[60:61], 0, s[6:7]
	global_load_dword v134, v[78:79], off
	v_lshl_add_u64 v[78:79], v[58:59], 0, s[6:7]
	global_load_dword v135, v[78:79], off
	v_lshl_add_u64 v[78:79], v[56:57], 0, s[6:7]
	global_load_dword v136, v[78:79], off
	v_lshl_add_u64 v[78:79], v[54:55], 0, s[6:7]
	global_load_dword v137, v[78:79], off
	v_lshl_add_u64 v[78:79], v[52:53], 0, s[6:7]
	global_load_dword v138, v[78:79], off
	v_lshl_add_u64 v[78:79], v[50:51], 0, s[6:7]
	global_load_dword v139, v[78:79], off
	s_add_u32 s6, s6, 0x64600
	s_addc_u32 s7, s7, 0
	v_lshl_add_u64 v[78:79], v[64:65], 0, s[6:7]
	global_load_dword v140, v[78:79], off
	v_lshl_add_u64 v[78:79], v[62:63], 0, s[6:7]
	global_load_dword v141, v[78:79], off
	v_lshl_add_u64 v[78:79], v[60:61], 0, s[6:7]
	global_load_dword v142, v[78:79], off
	v_lshl_add_u64 v[78:79], v[58:59], 0, s[6:7]
	global_load_dword v143, v[78:79], off
	v_lshl_add_u64 v[78:79], v[56:57], 0, s[6:7]
	global_load_dword v144, v[78:79], off
	v_lshl_add_u64 v[78:79], v[54:55], 0, s[6:7]
	global_load_dword v145, v[78:79], off
	v_lshl_add_u64 v[78:79], v[52:53], 0, s[6:7]
	global_load_dword v146, v[78:79], off
	v_lshl_add_u64 v[78:79], v[50:51], 0, s[6:7]
	global_load_dword v147, v[78:79], off
	s_add_u32 s6, s6, 0x64600
	s_addc_u32 s7, s7, 0
	v_lshl_add_u64 v[78:79], v[64:65], 0, s[6:7]
	global_load_dword v148, v[78:79], off
	v_lshl_add_u64 v[78:79], v[62:63], 0, s[6:7]
	global_load_dword v149, v[78:79], off
	v_lshl_add_u64 v[78:79], v[60:61], 0, s[6:7]
	global_load_dword v150, v[78:79], off
	v_lshl_add_u64 v[78:79], v[58:59], 0, s[6:7]
	global_load_dword v151, v[78:79], off
	v_lshl_add_u64 v[78:79], v[56:57], 0, s[6:7]
	global_load_dword v152, v[78:79], off
	v_lshl_add_u64 v[78:79], v[54:55], 0, s[6:7]
	global_load_dword v153, v[78:79], off
	v_lshl_add_u64 v[78:79], v[52:53], 0, s[6:7]
	global_load_dword v154, v[78:79], off
	v_lshl_add_u64 v[78:79], v[50:51], 0, s[6:7]
	global_load_dword v155, v[78:79], off
	s_add_u32 s6, s6, 0x64600
	s_addc_u32 s7, s7, 0
	v_lshl_add_u64 v[78:79], v[64:65], 0, s[6:7]
	global_load_dword v156, v[78:79], off
	v_lshl_add_u64 v[78:79], v[62:63], 0, s[6:7]
	global_load_dword v157, v[78:79], off
	v_lshl_add_u64 v[78:79], v[60:61], 0, s[6:7]
	global_load_dword v158, v[78:79], off
	v_lshl_add_u64 v[78:79], v[58:59], 0, s[6:7]
	global_load_dword v159, v[78:79], off
	v_lshl_add_u64 v[78:79], v[56:57], 0, s[6:7]
	global_load_dword v160, v[78:79], off
	v_lshl_add_u64 v[78:79], v[54:55], 0, s[6:7]
	global_load_dword v161, v[78:79], off
	v_lshl_add_u64 v[78:79], v[52:53], 0, s[6:7]
	global_load_dword v162, v[78:79], off
	v_lshl_add_u64 v[78:79], v[50:51], 0, s[6:7]
	global_load_dword v163, v[78:79], off
	s_or_b64 exec, exec, s[2:3]
	s_add_u32 s6, s6, 0x64600
	s_addc_u32 s7, s7, 0
	s_waitcnt vmcnt(31)
	ds_write_b32 v8, v132
	s_waitcnt vmcnt(30)
	ds_write_b32 v8, v133 offset:264
	s_waitcnt vmcnt(29)
	ds_write_b32 v8, v134 offset:528
	s_waitcnt vmcnt(28)
	ds_write_b32 v8, v135 offset:792
	s_waitcnt vmcnt(27)
	ds_write_b32 v8, v136 offset:1056
	s_waitcnt vmcnt(26)
	ds_write_b32 v8, v137 offset:1320
	s_waitcnt vmcnt(25)
	ds_write_b32 v8, v138 offset:1584
	s_waitcnt vmcnt(24)
	ds_write_b32 v8, v139 offset:1848
	s_waitcnt vmcnt(23)
	ds_write_b32 v8, v140 offset:2112
	s_waitcnt vmcnt(22)
	ds_write_b32 v8, v141 offset:2376
	s_waitcnt vmcnt(21)
	ds_write_b32 v8, v142 offset:2640
	s_waitcnt vmcnt(20)
	ds_write_b32 v8, v143 offset:2904
	s_waitcnt vmcnt(19)
	ds_write_b32 v8, v144 offset:3168
	s_waitcnt vmcnt(18)
	ds_write_b32 v8, v145 offset:3432
	s_waitcnt vmcnt(17)
	ds_write_b32 v8, v146 offset:3696
	s_waitcnt vmcnt(16)
	ds_write_b32 v8, v147 offset:3960
	s_waitcnt vmcnt(15)
	ds_write_b32 v8, v148 offset:4224
	s_waitcnt vmcnt(14)
	ds_write_b32 v8, v149 offset:4488
	s_waitcnt vmcnt(13)
	ds_write_b32 v8, v150 offset:4752
	s_waitcnt vmcnt(12)
	ds_write_b32 v8, v151 offset:5016
	s_waitcnt vmcnt(11)
	ds_write_b32 v8, v152 offset:5280
	s_waitcnt vmcnt(10)
	ds_write_b32 v8, v153 offset:5544
	s_waitcnt vmcnt(9)
	ds_write_b32 v8, v154 offset:5808
	s_waitcnt vmcnt(8)
	ds_write_b32 v8, v155 offset:6072
	s_waitcnt vmcnt(7)
	ds_write_b32 v8, v156 offset:6336
	s_waitcnt vmcnt(6)
	ds_write_b32 v8, v157 offset:6600
	s_waitcnt vmcnt(5)
	ds_write_b32 v8, v158 offset:6864
	s_waitcnt vmcnt(4)
	ds_write_b32 v8, v159 offset:7128
	s_waitcnt vmcnt(3)
	ds_write_b32 v8, v160 offset:7392
	s_waitcnt vmcnt(2)
	ds_write_b32 v8, v161 offset:7656
	s_waitcnt vmcnt(1)
	ds_write_b32 v8, v162 offset:7920
	s_waitcnt vmcnt(0)
	ds_write_b32 v8, v163 offset:8184
	v_add_u32_e32 v8, 0x2100, v8
	s_branch .LBB0_96

; #define LAS __attribute__((address_space(3)))
; #define LDS_WAIT() asm volatile("s_waitcnt lgkmcnt(0)" ::: "memory")
; __device__ __forceinline__ void tr_item(const float* W, int ldw, int src_col, int nvalid, int k0, bf16_t* WT, int ldt, int dst_row, int dst_k, LAS float* scr, int lane) {
; #pragma unroll 8
;     for (int i = 0; i < 32; ++i) { const int kk = 2 * i + (lane >> 5), c = lane & 31; scr[kk * 33 + c] = (c < nvalid) ? W[(size_t)(k0 + kk) * ldw + src_col + c] : 0.f; }
;     LDS_WAIT();
; __device__ __forceinline__ void convert_layer(const Ctx& C, int l) {
;     ...
;         if (r < 1792) { const int kb = r / 112, nb = r % 112; int src = 0, nv = 0;
;             if (nb < 88) { src = nb * 32; nv = 32; } else if (nb < 104) { src = 2840 + (nb - 88) * 32; nv = 32; } else if (nb == 104) { src = 2816; nv = 24; }
;             tr_item(INF(10, l, DM * 6424), 6424, src, nv, kb * 64, (bf16_t*)(ws + WS_WMIX), DM, nb * 32, 0, scr, lane); continue; } r -= 1792;
.LBB0_1470:
	v_mov_b32_e32 v132, 0
	v_mov_b32_e32 v133, 0
	v_mov_b32_e32 v134, 0
	v_mov_b32_e32 v135, 0
	v_mov_b32_e32 v136, 0
	v_mov_b32_e32 v137, 0
	v_mov_b32_e32 v138, 0
	v_mov_b32_e32 v139, 0
	v_mov_b32_e32 v140, 0
	v_mov_b32_e32 v141, 0
	v_mov_b32_e32 v142, 0
	v_mov_b32_e32 v143, 0
	v_mov_b32_e32 v144, 0
	v_mov_b32_e32 v145, 0
	v_mov_b32_e32 v146, 0
	v_mov_b32_e32 v147, 0
	v_mov_b32_e32 v148, 0
	v_mov_b32_e32 v149, 0
	v_mov_b32_e32 v150, 0
	v_mov_b32_e32 v151, 0
	v_mov_b32_e32 v152, 0
	v_mov_b32_e32 v153, 0
	v_mov_b32_e32 v154, 0
	v_mov_b32_e32 v155, 0
	v_mov_b32_e32 v156, 0
	v_mov_b32_e32 v157, 0
	v_mov_b32_e32 v158, 0
	v_mov_b32_e32 v159, 0
	v_mov_b32_e32 v160, 0
	v_mov_b32_e32 v161, 0
	v_mov_b32_e32 v162, 0
	v_mov_b32_e32 v163, 0
	s_and_saveexec_b64 s[2:3], s[12:13]
	v_lshl_add_u64 v[78:79], v[64:65], 0, s[18:19]
	global_load_dword v132, v[78:79], off
	v_lshl_add_u64 v[78:79], v[62:63], 0, s[18:19]
	global_load_dword v133, v[78:79], off
	v_lshl_add_u64 v[78:79], v[60:61], 0, s[18:19]
	global_load_dword v134, v[78:79], off
	v_lshl_add_u64 v[78:79], v[58:59], 0, s[18:19]
	global_load_dword v135, v[78:79], off
	v_lshl_add_u64 v[78:79], v[56:57], 0, s[18:19]
	global_load_dword v136, v[78:79], off
	v_lshl_add_u64 v[78:79], v[54:55], 0, s[18:19]
	global_load_dword v137, v[78:79], off
	v_lshl_add_u64 v[78:79], v[52:53], 0, s[18:19]
	global_load_dword v138, v[78:79], off
	v_lshl_add_u64 v[78:79], v[50:51], 0, s[18:19]
	global_load_dword v139, v[78:79], off
	s_add_u32 s18, s18, 0x64600
	s_addc_u32 s19, s19, 0
	v_lshl_add_u64 v[78:79], v[64:65], 0, s[18:19]
	global_load_dword v140, v[78:79], off
	v_lshl_add_u64 v[78:79], v[62:63], 0, s[18:19]
	global_load_dword v141, v[78:79], off
	v_lshl_add_u64 v[78:79], v[60:61], 0, s[18:19]
	global_load_dword v142, v[78:79], off
	v_lshl_add_u64 v[78:79], v[58:59], 0, s[18:19]
	global_load_dword v143, v[78:79], off
	v_lshl_add_u64 v[78:79], v[56:57], 0, s[18:19]
	global_load_dword v144, v[78:79], off
	v_lshl_add_u64 v[78:79], v[54:55], 0, s[18:19]
	global_load_dword v145, v[78:79], off
	v_lshl_add_u64 v[78:79], v[52:53], 0, s[18:19]
	global_load_dword v146, v[78:79], off
	v_lshl_add_u64 v[78:79], v[50:51], 0, s[18:19]
	global_load_dword v147, v[78:79], off
	s_add_u32 s18, s18, 0x64600
	s_addc_u32 s19, s19, 0
	v_lshl_add_u64 v[78:79], v[64:65], 0, s[18:19]
	global_load_dword v148, v[78:79], off
	v_lshl_add_u64 v[78:79], v[62:63], 0, s[18:19]
	global_load_dword v149, v[78:79], off
	v_lshl_add_u64 v[78:79], v[60:61], 0, s[18:19]
	global_load_dword v150, v[78:79], off
	v_lshl_add_u64 v[78:79], v[58:59], 0, s[18:19]
	global_load_dword v151, v[78:79], off
	v_lshl_add_u64 v[78:79], v[56:57], 0, s[18:19]
	global_load_dword v152, v[78:79], off
	v_lshl_add_u64 v[78:79], v[54:55], 0, s[18:19]
	global_load_dword v153, v[78:79], off
	v_lshl_add_u64 v[78:79], v[52:53], 0, s[18:19]
	global_load_dword v154, v[78:79], off
	v_lshl_add_u64 v[78:79], v[50:51], 0, s[18:19]
	global_load_dword v155, v[78:79], off
	s_add_u32 s18, s18, 0x64600
	s_addc_u32 s19, s19, 0
	v_lshl_add_u64 v[78:79], v[64:65], 0, s[18:19]
	global_load_dword v156, v[78:79], off
	v_lshl_add_u64 v[78:79], v[62:63], 0, s[18:19]
	global_load_dword v157, v[78:79], off
	v_lshl_add_u64 v[78:79], v[60:61], 0, s[18:19]
	global_load_dword v158, v[78:79], off
	v_lshl_add_u64 v[78:79], v[58:59], 0, s[18:19]
	global_load_dword v159, v[78:79], off
	v_lshl_add_u64 v[78:79], v[56:57], 0, s[18:19]
	global_load_dword v160, v[78:79], off
	v_lshl_add_u64 v[78:79], v[54:55], 0, s[18:19]
	global_load_dword v161, v[78:79], off
	v_lshl_add_u64 v[78:79], v[52:53], 0, s[18:19]
	global_load_dword v162, v[78:79], off
	v_lshl_add_u64 v[78:79], v[50:51], 0, s[18:19]
	global_load_dword v163, v[78:79], off
	s_or_b64 exec, exec, s[2:3]
	s_add_u32 s18, s18, 0x64600
	s_addc_u32 s19, s19, 0
	s_waitcnt vmcnt(31)
	ds_write_b32 v0, v132
	s_waitcnt vmcnt(30)
	ds_write_b32 v0, v133 offset:264
	s_waitcnt vmcnt(29)
	ds_write_b32 v0, v134 offset:528
	s_waitcnt vmcnt(28)
	ds_write_b32 v0, v135 offset:792
	s_waitcnt vmcnt(27)
	ds_write_b32 v0, v136 offset:1056
	s_waitcnt vmcnt(26)
	ds_write_b32 v0, v137 offset:1320
	s_waitcnt vmcnt(25)
	ds_write_b32 v0, v138 offset:1584
	s_waitcnt vmcnt(24)
	ds_write_b32 v0, v139 offset:1848
	s_waitcnt vmcnt(23)
	ds_write_b32 v0, v140 offset:2112
	s_waitcnt vmcnt(22)
	ds_write_b32 v0, v141 offset:2376
	s_waitcnt vmcnt(21)
	ds_write_b32 v0, v142 offset:2640
	s_waitcnt vmcnt(20)
	ds_write_b32 v0, v143 offset:2904
	s_waitcnt vmcnt(19)
	ds_write_b32 v0, v144 offset:3168
	s_waitcnt vmcnt(18)
	ds_write_b32 v0, v145 offset:3432
	s_waitcnt vmcnt(17)
	ds_write_b32 v0, v146 offset:3696
	s_waitcnt vmcnt(16)
	ds_write_b32 v0, v147 offset:3960
	s_waitcnt vmcnt(15)
	ds_write_b32 v0, v148 offset:4224
	s_waitcnt vmcnt(14)
	ds_write_b32 v0, v149 offset:4488
	s_waitcnt vmcnt(13)
	ds_write_b32 v0, v150 offset:4752
	s_waitcnt vmcnt(12)
	ds_write_b32 v0, v151 offset:5016
	s_waitcnt vmcnt(11)
	ds_write_b32 v0, v152 offset:5280
	s_waitcnt vmcnt(10)
	ds_write_b32 v0, v153 offset:5544
	s_waitcnt vmcnt(9)
	ds_write_b32 v0, v154 offset:5808
	s_waitcnt vmcnt(8)
	ds_write_b32 v0, v155 offset:6072
	s_waitcnt vmcnt(7)
	ds_write_b32 v0, v156 offset:6336
	s_waitcnt vmcnt(6)
	ds_write_b32 v0, v157 offset:6600
	s_waitcnt vmcnt(5)
	ds_write_b32 v0, v158 offset:6864
	s_waitcnt vmcnt(4)
	ds_write_b32 v0, v159 offset:7128
	s_waitcnt vmcnt(3)
	ds_write_b32 v0, v160 offset:7392
	s_waitcnt vmcnt(2)
	ds_write_b32 v0, v161 offset:7656
	s_waitcnt vmcnt(1)
	ds_write_b32 v0, v162 offset:7920
	s_waitcnt vmcnt(0)
	ds_write_b32 v0, v163 offset:8184
	v_add_u32_e32 v0, 0x2100, v0
	s_branch .LBB0_1487
